# E40: P5 epilogue residual-x loads batched (28 in flight, counted vmcnt, saddr form) instead of 32 serial load-wait-store round trips
# baseline (speedup 1.0000x reference)
; template <bool SWAP, class Epi>
; DEVINL void gemm_tile(const Params& p, const bf16_t* __restrict__ A0, const bf16_t* __restrict__ A1, int ksplit, int lda,
;                       const bf16_t* __restrict__ Bt, int ldb, int nt, char* shmc, Epi epi) {
;     ...
; #pragma unroll
;   for (int ai = 0; ai < 2; ++ai)
; #pragma unroll
;     for (int bj = 0; bj < 2; ++bj)
; #pragma unroll
;       for (int m = 0; m < 4; ++m)
; #pragma unroll
;         for (int n = 0; n < 2; ++n) {
;           if (SWAP) epi(ai * HALF + wr * 64 + m * 16 + fr, bj * HALF + wc * 32 + n * 16 + fq * 4, acc[ai][bj][m][n]);
;           else      epi(ai * HALF + wr * 64 + m * 16 + fq * 4, bj * HALF + wc * 32 + n * 16 + fr, acc[ai][bj][m][n]);
;         }
; DEVINL void phase_gemm3(const Params& p, char* lds) {
;     ...
;     const float* xr = p.x + (size_t)brow * DM + pn * 256; float* od = p.out + (size_t)brow * DM + pn * 256;
;     gemm_tile<true>(p, YM + (size_t)brow * 1024, YN + (size_t)brow * 1024, 16, 1024, WoutT + (size_t)pn * 256 * 2048, 2048, 2048 / BK, lds,
;                     [=](int row, int col, f32x4 v) {
;       const f32x4 xv = *reinterpret_cast<const f32x4*>(xr + (size_t)row * DM + col);
;       f32x4 o = {xv[0] + v[0], xv[1] + v[1], xv[2] + v[2], xv[3] + v[3]};
;       *reinterpret_cast<f32x4*>(od + (size_t)row * DM + col) = o;
;     });
.LBB0_669:
	s_or_b64 exec, exec, s[30:31]
	s_lshl_b64 s[28:29], s[28:29], 2
	s_add_u32 s6, s36, s28
	s_addc_u32 s34, s37, s29
	s_lshl_b32 s26, s26, 8
	s_ashr_i32 s27, s26, 31
	s_lshl_b64 s[30:31], s[26:27], 2
	s_add_u32 s26, s6, s30
	s_addc_u32 s27, s34, s31
	s_add_u32 s6, s70, s28
	s_addc_u32 s29, s71, s29
	s_add_u32 s28, s6, s30
	s_addc_u32 s29, s29, s31
	v_lshl_or_b32 v176, v199, 7, v200
	v_lshl_add_u32 v128, v178, 12, v176
	v_add_u32_e32 v129, 0x10000, v128
	v_add_u32_e32 v130, 0x20000, v128
	v_add_u32_e32 v131, 0x30000, v128
	v_add_u32_e32 v132, 0x80000, v128
	v_add_u32_e32 v133, 0x90000, v128
	v_add_u32_e32 v134, 0xa0000, v128
	v_add_u32_e32 v135, 0xb0000, v128
	global_load_dwordx4 v[136:139], v128, s[26:27]
	global_load_dwordx4 v[140:143], v128, s[26:27] offset:64
	global_load_dwordx4 v[144:147], v129, s[26:27]
	global_load_dwordx4 v[148:151], v129, s[26:27] offset:64
	global_load_dwordx4 v[152:155], v130, s[26:27]
	global_load_dwordx4 v[156:159], v130, s[26:27] offset:64
	global_load_dwordx4 v[160:163], v131, s[26:27]
	global_load_dwordx4 v[164:167], v131, s[26:27] offset:64
	global_load_dwordx4 v[168:171], v128, s[26:27] offset:512
	global_load_dwordx4 v[172:175], v128, s[26:27] offset:576
	global_load_dwordx4 v[180:183], v129, s[26:27] offset:512
	global_load_dwordx4 v[184:187], v129, s[26:27] offset:576
	global_load_dwordx4 v[188:191], v130, s[26:27] offset:512
	global_load_dwordx4 v[192:195], v130, s[26:27] offset:576
	global_load_dwordx4 v[200:203], v131, s[26:27] offset:512
	global_load_dwordx4 v[204:207], v131, s[26:27] offset:576
	global_load_dwordx4 v[208:211], v132, s[26:27]
	global_load_dwordx4 v[212:215], v132, s[26:27] offset:64
	global_load_dwordx4 v[216:219], v133, s[26:27]
	global_load_dwordx4 v[220:223], v133, s[26:27] offset:64
	global_load_dwordx4 v[224:227], v134, s[26:27]
	global_load_dwordx4 v[228:231], v134, s[26:27] offset:64
	global_load_dwordx4 v[232:235], v135, s[26:27]
	global_load_dwordx4 v[236:239], v135, s[26:27] offset:64
	global_load_dwordx4 v[240:243], v132, s[26:27] offset:512
	global_load_dwordx4 v[244:247], v132, s[26:27] offset:576
	global_load_dwordx4 v[248:251], v133, s[26:27] offset:512
	global_load_dwordx4 v[252:255], v133, s[26:27] offset:576
	s_waitcnt vmcnt(27)
	v_pk_add_f32 v[124:125], v[124:125], v[136:137]
	v_pk_add_f32 v[126:127], v[126:127], v[138:139]
	global_store_dwordx4 v128, v[124:127], s[28:29]
	global_load_dwordx4 v[136:139], v134, s[26:27] offset:512
	s_waitcnt vmcnt(28)
	v_pk_add_f32 v[120:121], v[120:121], v[140:141]
	v_pk_add_f32 v[122:123], v[122:123], v[142:143]
	global_store_dwordx4 v128, v[120:123], s[28:29] offset:64
	global_load_dwordx4 v[140:143], v134, s[26:27] offset:576
	s_waitcnt vmcnt(29)
	v_pk_add_f32 v[116:117], v[116:117], v[144:145]
	v_pk_add_f32 v[118:119], v[118:119], v[146:147]
	global_store_dwordx4 v129, v[116:119], s[28:29]
	global_load_dwordx4 v[144:147], v135, s[26:27] offset:512
	s_waitcnt vmcnt(30)
	v_pk_add_f32 v[112:113], v[112:113], v[148:149]
	v_pk_add_f32 v[114:115], v[114:115], v[150:151]
	global_store_dwordx4 v129, v[112:115], s[28:29] offset:64
	global_load_dwordx4 v[148:151], v135, s[26:27] offset:576
	s_waitcnt vmcnt(31)
	v_pk_add_f32 v[108:109], v[108:109], v[152:153]
	v_pk_add_f32 v[110:111], v[110:111], v[154:155]
	global_store_dwordx4 v130, v[108:111], s[28:29]
	s_waitcnt vmcnt(31)
	v_pk_add_f32 v[104:105], v[104:105], v[156:157]
	v_pk_add_f32 v[106:107], v[106:107], v[158:159]
	global_store_dwordx4 v130, v[104:107], s[28:29] offset:64
	s_waitcnt vmcnt(31)
	v_pk_add_f32 v[100:101], v[100:101], v[160:161]
	v_pk_add_f32 v[102:103], v[102:103], v[162:163]
	global_store_dwordx4 v131, v[100:103], s[28:29]
	s_waitcnt vmcnt(31)
	v_pk_add_f32 v[92:93], v[92:93], v[164:165]
	v_pk_add_f32 v[94:95], v[94:95], v[166:167]
	global_store_dwordx4 v131, v[92:95], s[28:29] offset:64
	s_waitcnt vmcnt(31)
	v_pk_add_f32 v[96:97], v[96:97], v[168:169]
	v_pk_add_f32 v[98:99], v[98:99], v[170:171]
	global_store_dwordx4 v128, v[96:99], s[28:29] offset:512
	s_waitcnt vmcnt(31)
; DEVINL void phase_gemm3(const Params& p, char* lds) {
;     ...
;   for (int t = blockIdx.x; t < (SEQ / 256) * 4; t += gridDim.x) {
;     ...
;       const f32x4 xv = *reinterpret_cast<const f32x4*>(xr + (size_t)row * DM + col);
;       f32x4 o = {xv[0] + v[0], xv[1] + v[1], xv[2] + v[2], xv[3] + v[3]};
;       *reinterpret_cast<f32x4*>(od + (size_t)row * DM + col) = o;
;     });
	v_pk_add_f32 v[88:89], v[88:89], v[172:173]
	v_pk_add_f32 v[90:91], v[90:91], v[174:175]
	global_store_dwordx4 v128, v[88:91], s[28:29] offset:576
	s_waitcnt vmcnt(31)
	v_pk_add_f32 v[84:85], v[84:85], v[180:181]
	v_pk_add_f32 v[86:87], v[86:87], v[182:183]
	global_store_dwordx4 v129, v[84:87], s[28:29] offset:512
	s_waitcnt vmcnt(31)
	v_pk_add_f32 v[80:81], v[80:81], v[184:185]
	v_pk_add_f32 v[82:83], v[82:83], v[186:187]
	global_store_dwordx4 v129, v[80:83], s[28:29] offset:576
	s_waitcnt vmcnt(31)
	v_pk_add_f32 v[76:77], v[76:77], v[188:189]
	v_pk_add_f32 v[78:79], v[78:79], v[190:191]
	global_store_dwordx4 v130, v[76:79], s[28:29] offset:512
	s_waitcnt vmcnt(31)
	v_pk_add_f32 v[72:73], v[72:73], v[192:193]
	v_pk_add_f32 v[74:75], v[74:75], v[194:195]
	global_store_dwordx4 v130, v[72:75], s[28:29] offset:576
	s_waitcnt vmcnt(31)
	v_pk_add_f32 v[68:69], v[68:69], v[200:201]
	v_pk_add_f32 v[70:71], v[70:71], v[202:203]
	global_store_dwordx4 v131, v[68:71], s[28:29] offset:512
	s_waitcnt vmcnt(31)
	v_pk_add_f32 v[60:61], v[60:61], v[204:205]
	v_pk_add_f32 v[62:63], v[62:63], v[206:207]
	global_store_dwordx4 v131, v[60:63], s[28:29] offset:576
	s_waitcnt vmcnt(31)
	v_pk_add_f32 v[64:65], v[64:65], v[208:209]
	v_pk_add_f32 v[66:67], v[66:67], v[210:211]
	global_store_dwordx4 v132, v[64:67], s[28:29]
	s_waitcnt vmcnt(31)
	v_pk_add_f32 v[56:57], v[56:57], v[212:213]
	v_pk_add_f32 v[58:59], v[58:59], v[214:215]
	global_store_dwordx4 v132, v[56:59], s[28:29] offset:64
	s_waitcnt vmcnt(31)
	v_pk_add_f32 v[52:53], v[52:53], v[216:217]
	v_pk_add_f32 v[54:55], v[54:55], v[218:219]
	global_store_dwordx4 v133, v[52:55], s[28:29]
	s_waitcnt vmcnt(31)
	v_pk_add_f32 v[48:49], v[48:49], v[220:221]
	v_pk_add_f32 v[50:51], v[50:51], v[222:223]
	global_store_dwordx4 v133, v[48:51], s[28:29] offset:64
	s_waitcnt vmcnt(31)
	v_pk_add_f32 v[44:45], v[44:45], v[224:225]
	v_pk_add_f32 v[46:47], v[46:47], v[226:227]
	global_store_dwordx4 v134, v[44:47], s[28:29]
	s_waitcnt vmcnt(31)
	v_pk_add_f32 v[40:41], v[40:41], v[228:229]
	v_pk_add_f32 v[42:43], v[42:43], v[230:231]
	global_store_dwordx4 v134, v[40:43], s[28:29] offset:64
	s_waitcnt vmcnt(31)
	v_pk_add_f32 v[36:37], v[36:37], v[232:233]
	v_pk_add_f32 v[38:39], v[38:39], v[234:235]
	global_store_dwordx4 v135, v[36:39], s[28:29]
	s_waitcnt vmcnt(31)
	v_pk_add_f32 v[32:33], v[32:33], v[236:237]
	v_pk_add_f32 v[34:35], v[34:35], v[238:239]
	global_store_dwordx4 v135, v[32:35], s[28:29] offset:64
	s_waitcnt vmcnt(31)
	v_pk_add_f32 v[28:29], v[28:29], v[240:241]
	v_pk_add_f32 v[30:31], v[30:31], v[242:243]
	global_store_dwordx4 v132, v[28:31], s[28:29] offset:512
	s_waitcnt vmcnt(31)
	v_pk_add_f32 v[24:25], v[24:25], v[244:245]
	v_pk_add_f32 v[26:27], v[26:27], v[246:247]
	global_store_dwordx4 v132, v[24:27], s[28:29] offset:576
	s_waitcnt vmcnt(31)
	v_pk_add_f32 v[20:21], v[20:21], v[248:249]
	v_pk_add_f32 v[22:23], v[22:23], v[250:251]
	global_store_dwordx4 v133, v[20:23], s[28:29] offset:512
	s_waitcnt vmcnt(31)
	v_pk_add_f32 v[16:17], v[16:17], v[252:253]
	v_pk_add_f32 v[18:19], v[18:19], v[254:255]
	global_store_dwordx4 v133, v[16:19], s[28:29] offset:576
	s_waitcnt vmcnt(30)
	v_pk_add_f32 v[12:13], v[12:13], v[136:137]
	v_pk_add_f32 v[14:15], v[14:15], v[138:139]
	global_store_dwordx4 v134, v[12:15], s[28:29] offset:512
	s_waitcnt vmcnt(29)
	v_pk_add_f32 v[8:9], v[8:9], v[140:141]
	v_pk_add_f32 v[10:11], v[10:11], v[142:143]
	global_store_dwordx4 v134, v[8:11], s[28:29] offset:576
	s_waitcnt vmcnt(28)
	v_pk_add_f32 v[4:5], v[4:5], v[144:145]
	v_pk_add_f32 v[6:7], v[6:7], v[146:147]
	global_store_dwordx4 v135, v[4:7], s[28:29] offset:512
	s_waitcnt vmcnt(27)
	v_pk_add_f32 v[0:1], v[0:1], v[148:149]
	v_pk_add_f32 v[2:3], v[2:3], v[150:151]
	global_store_dwordx4 v135, v[0:3], s[28:29] offset:576
	s_load_dword s6, s[0:1], 0x0
	s_waitcnt lgkmcnt(0)
	s_add_i32 s2, s6, s2
	s_cmpk_lt_i32 s2, 0x100
	s_cbranch_scc0 .LBB0_680
